# tile order panel groups (6,6,5) for all six GEMM types
# baseline (speedup 1.0000x reference)
.LBB0_679:
	s_cmp_ge_u32 s3, 48
	s_cbranch_scc1 .Lto_g1_b0
	s_sub_u32 s99, s3, 0
	s_mul_hi_u32 s98, s99, 0xaaaaaaab
	s_lshr_b32 s98, s98, 2
	s_mul_i32 s100, s98, 6
	s_sub_u32 s99, s99, s100
	s_branch .Lto_j_b0
.Lto_g1_b0:
	s_cmp_ge_u32 s3, 96
	s_cbranch_scc1 .Lto_g2_b0
	s_sub_u32 s99, s3, 48
	s_mul_hi_u32 s98, s99, 0xaaaaaaab
	s_lshr_b32 s98, s98, 2
	s_mul_i32 s100, s98, 6
	s_sub_u32 s99, s99, s100
	s_add_u32 s99, s99, 6
	s_branch .Lto_j_b0
.Lto_g2_b0:
	s_sub_u32 s99, s3, 96
	s_mul_hi_u32 s98, s99, 0xcccccccd
	s_lshr_b32 s98, s98, 2
	s_mul_i32 s100, s98, 5
	s_sub_u32 s99, s99, s100
	s_add_u32 s99, s99, 12

.LBB0_1934:
	s_cmp_ge_u32 s12, 48
	s_cbranch_scc1 .Lto_g1_b5
	s_sub_u32 s99, s12, 0
	s_mul_hi_u32 s98, s99, 0xaaaaaaab
	s_lshr_b32 s98, s98, 2
	s_mul_i32 s100, s98, 6
	s_sub_u32 s99, s99, s100
	s_branch .Lto_j_b5
.Lto_g1_b5:
	s_cmp_ge_u32 s12, 96
	s_cbranch_scc1 .Lto_g2_b5
	s_sub_u32 s99, s12, 48
	s_mul_hi_u32 s98, s99, 0xaaaaaaab
	s_lshr_b32 s98, s98, 2
	s_mul_i32 s100, s98, 6
	s_sub_u32 s99, s99, s100
	s_add_u32 s99, s99, 6
	s_branch .Lto_j_b5
.Lto_g2_b5:
	s_sub_u32 s99, s12, 96
	s_mul_hi_u32 s98, s99, 0xcccccccd
	s_lshr_b32 s98, s98, 2
	s_mul_i32 s100, s98, 5
	s_sub_u32 s99, s99, s100
	s_add_u32 s99, s99, 12
